# RESID epilogue hand-pipelined: 12 x-tile loads in flight with counted vmcnt instead of 16 serialized load-wait-store
# speedup vs baseline: 1.0487x; 1.0439x over previous
; __device__ __forceinline__ unsigned cvt_pk_bf16(float lo, float hi) { unsigned r; asm volatile("v_cvt_pk_bf16_f32 %0, %1, %2" : "=v"(r) : "v"(lo), "v"(hi)); return r; }
; __device__ __forceinline__ float bflo(unsigned w) { return __uint_as_float(w << 16); }
; __device__ __forceinline__ float bfhi(unsigned w) { return __uint_as_float(w & 0xffff0000u); }
; __device__ __forceinline__ void epi_resid(const f32x4 (&acc)[2][2][4][2], const Unit& u, char* Cb, int ldc, const float* bias, int wr, int wc, int fr, int fq) {
;     const int col0 = u.pn * BM + wc * 32 + 8 * fq;
;     bf16_t* base = (bf16_t*)Cb + (long)(u.pm * BM + wr * 64 + fr) * ldc + col0;
; #pragma unroll
;     for (int bj = 0; bj < 2; ++bj) {
;         const f32x4 b0 = bias ? *(const f32x4*)(bias + col0 + bj * HALF) : (f32x4){0.f, 0.f, 0.f, 0.f};
;         const f32x4 b1 = bias ? *(const f32x4*)(bias + col0 + bj * HALF + 4) : (f32x4){0.f, 0.f, 0.f, 0.f};
; #pragma unroll
;         for (int ai = 0; ai < 2; ++ai)
; #pragma unroll
;             for (int m = 0; m < 4; ++m) { u32x4* q = (u32x4*)(base + (long)(ai * HALF + m * 16) * ldc + bj * HALF);
;                 const u32x4 x = *q; const f32x4 a0 = acc[ai][bj][m][0], a1 = acc[ai][bj][m][1];
;                 u32x4 w;
;                 w.x = cvt_pk_bf16(bflo(x.x) + a0[0] + b0[0], bfhi(x.x) + a0[1] + b0[1]); w.y = cvt_pk_bf16(bflo(x.y) + a0[2] + b0[2], bfhi(x.y) + a0[3] + b0[3]);
;                 w.z = cvt_pk_bf16(bflo(x.z) + a1[0] + b1[0], bfhi(x.z) + a1[1] + b1[1]); w.w = cvt_pk_bf16(bflo(x.w) + a1[2] + b1[2], bfhi(x.w) + a1[3] + b1[3]);
;                 *q = w; } }
; }
.LBB0_544:
	s_and_b64 vcc, exec, s[2:3]
	s_cbranch_vccz .LBB0_563
	s_cmp_gt_i32 s45, 0
	s_mov_b64 s[2:3], -1
	s_cbranch_scc0 .LBB0_561
	s_cmp_gt_i32 s45, 1
	s_cbranch_scc0 .LBB0_558
	s_cmp_eq_u32 s45, 2
	s_mov_b64 s[72:73], -1
	s_cbranch_scc0 .LBB0_557
	s_load_dwordx2 s[8:9], s[90:91], 0x1d8
	s_load_dword s52, s[90:91], 0x228
	v_lshl_or_b32 v12, s61, 8, v239
	v_ashrrev_i32_e32 v13, 31, v12
	v_lshl_add_u32 v10, s68, 8, v166
	v_mov_b32_e32 v206, 0
	v_mov_b32_e32 v207, 0
	v_mov_b32_e32 v208, 0
	v_mov_b32_e32 v209, 0
	v_mov_b32_e32 v242, 0
	v_mov_b32_e32 v243, 0
	v_mov_b32_e32 v244, 0
	v_mov_b32_e32 v245, 0
	v_mov_b32_e32 v246, 0
	v_mov_b32_e32 v247, 0
	v_mov_b32_e32 v248, 0
	v_mov_b32_e32 v249, 0
	v_mov_b32_e32 v250, 0
	v_mov_b32_e32 v251, 0
	v_mov_b32_e32 v252, 0
	v_mov_b32_e32 v253, 0
	s_waitcnt lgkmcnt(0)
	v_mad_i64_i32 v[220:221], s[12:13], s52, v10, 0
	s_ashr_i32 s53, s52, 31
	s_lshl_b64 s[14:15], s[52:53], 5
	v_lshl_add_u64 v[220:221], v[220:221], 1, s[46:47]
	v_lshl_add_u64 v[220:221], v[12:13], 1, v[220:221]
	s_mul_hi_i32 s3, s52, 0xa0
	s_mul_i32 s2, s52, 0xa0
	s_cmp_eq_u64 s[8:9], 0
	s_cbranch_scc1 .Lres_nobias
	v_lshl_add_u64 v[226:227], v[12:13], 2, s[8:9]
	global_load_dwordx4 v[206:209], v[226:227], off
	global_load_dwordx4 v[242:245], v[226:227], off offset:16
	global_load_dwordx4 v[246:249], v[226:227], off offset:512
	global_load_dwordx4 v[250:253], v[226:227], off offset:528
.Lres_nobias:
	global_load_dwordx4 v[134:137], v[220:221], off
	v_lshl_add_u64 v[222:223], v[220:221], 0, s[14:15]
	global_load_dwordx4 v[138:141], v[222:223], off
	v_lshl_add_u64 v[222:223], v[222:223], 0, s[14:15]
	global_load_dwordx4 v[142:145], v[222:223], off
	v_lshl_add_u64 v[222:223], v[222:223], 0, s[14:15]
	global_load_dwordx4 v[146:149], v[222:223], off
	v_lshl_add_u64 v[222:223], v[222:223], 0, s[2:3]
	global_load_dwordx4 v[150:153], v[222:223], off
	v_lshl_add_u64 v[222:223], v[222:223], 0, s[14:15]
	global_load_dwordx4 v[154:157], v[222:223], off
	v_lshl_add_u64 v[222:223], v[222:223], 0, s[14:15]
	global_load_dwordx4 v[182:185], v[222:223], off
	v_lshl_add_u64 v[222:223], v[222:223], 0, s[14:15]
	global_load_dwordx4 v[186:189], v[222:223], off
	global_load_dwordx4 v[190:193], v[220:221], off offset:256
	v_lshl_add_u64 v[222:223], v[220:221], 0, s[14:15]
	global_load_dwordx4 v[194:197], v[222:223], off offset:256
	v_lshl_add_u64 v[222:223], v[222:223], 0, s[14:15]
	global_load_dwordx4 v[198:201], v[222:223], off offset:256
	v_lshl_add_u64 v[222:223], v[222:223], 0, s[14:15]
	global_load_dwordx4 v[202:205], v[222:223], off offset:256
	v_mov_b64_e32 v[224:225], v[220:221]
	s_waitcnt vmcnt(11)
	v_lshlrev_b32_e32 v10, 16, v134
	v_and_b32_e32 v134, 0xffff0000, v134
	v_add_f32_e32 v10, v130, v10
	v_add_f32_e32 v134, v131, v134
	v_add_f32_e32 v10, v206, v10
	v_add_f32_e32 v134, v207, v134
	v_cvt_pk_bf16_f32 v134, v10, v134
	v_lshlrev_b32_e32 v10, 16, v135
	v_and_b32_e32 v135, 0xffff0000, v135
	v_add_f32_e32 v10, v132, v10
	v_add_f32_e32 v135, v133, v135
	v_add_f32_e32 v10, v208, v10
	v_add_f32_e32 v135, v209, v135
	v_cvt_pk_bf16_f32 v135, v10, v135
	v_lshlrev_b32_e32 v10, 16, v136
	v_and_b32_e32 v136, 0xffff0000, v136
	v_add_f32_e32 v10, v126, v10
	v_add_f32_e32 v136, v127, v136
	v_add_f32_e32 v10, v242, v10
	v_add_f32_e32 v136, v243, v136
	v_cvt_pk_bf16_f32 v136, v10, v136
	v_lshlrev_b32_e32 v10, 16, v137
	v_and_b32_e32 v137, 0xffff0000, v137
	v_add_f32_e32 v10, v128, v10
	v_add_f32_e32 v137, v129, v137
	v_add_f32_e32 v10, v244, v10
	v_add_f32_e32 v137, v245, v137
	v_cvt_pk_bf16_f32 v137, v10, v137
	global_store_dwordx4 v[224:225], v[134:137], off
	v_lshl_add_u64 v[224:225], v[224:225], 0, s[14:15]
	s_nop 0
	v_lshl_add_u64 v[222:223], v[222:223], 0, s[2:3]
	global_load_dwordx4 v[134:137], v[222:223], off offset:256
	s_waitcnt vmcnt(12)
	v_lshlrev_b32_e32 v10, 16, v138
	v_and_b32_e32 v138, 0xffff0000, v138
	v_add_f32_e32 v10, v114, v10
	v_add_f32_e32 v138, v115, v138
	v_add_f32_e32 v10, v206, v10
	v_add_f32_e32 v138, v207, v138
	v_cvt_pk_bf16_f32 v138, v10, v138
	v_lshlrev_b32_e32 v10, 16, v139
	v_and_b32_e32 v139, 0xffff0000, v139
	v_add_f32_e32 v10, v116, v10
	v_add_f32_e32 v139, v117, v139
	v_add_f32_e32 v10, v208, v10
	v_add_f32_e32 v139, v209, v139
	v_cvt_pk_bf16_f32 v139, v10, v139
	v_lshlrev_b32_e32 v10, 16, v140
	v_and_b32_e32 v140, 0xffff0000, v140
	v_add_f32_e32 v10, v110, v10
	v_add_f32_e32 v140, v111, v140
	v_add_f32_e32 v10, v242, v10
	v_add_f32_e32 v140, v243, v140
	v_cvt_pk_bf16_f32 v140, v10, v140
	v_lshlrev_b32_e32 v10, 16, v141
	v_and_b32_e32 v141, 0xffff0000, v141
	v_add_f32_e32 v10, v112, v10
	v_add_f32_e32 v141, v113, v141
	v_add_f32_e32 v10, v244, v10
	v_add_f32_e32 v141, v245, v141
	v_cvt_pk_bf16_f32 v141, v10, v141
	global_store_dwordx4 v[224:225], v[138:141], off
	v_lshl_add_u64 v[224:225], v[224:225], 0, s[14:15]
	s_nop 0
	v_lshl_add_u64 v[222:223], v[222:223], 0, s[14:15]
	global_load_dwordx4 v[138:141], v[222:223], off offset:256
	s_waitcnt vmcnt(13)
	v_lshlrev_b32_e32 v10, 16, v142
	v_and_b32_e32 v142, 0xffff0000, v142
	v_add_f32_e32 v10, v98, v10
	v_add_f32_e32 v142, v99, v142
	v_add_f32_e32 v10, v206, v10
	v_add_f32_e32 v142, v207, v142
	v_cvt_pk_bf16_f32 v142, v10, v142
	v_lshlrev_b32_e32 v10, 16, v143
	v_and_b32_e32 v143, 0xffff0000, v143
	v_add_f32_e32 v10, v100, v10
	v_add_f32_e32 v143, v101, v143
	v_add_f32_e32 v10, v208, v10
	v_add_f32_e32 v143, v209, v143
	v_cvt_pk_bf16_f32 v143, v10, v143
	v_lshlrev_b32_e32 v10, 16, v144
	v_and_b32_e32 v144, 0xffff0000, v144
	v_add_f32_e32 v10, v94, v10
	v_add_f32_e32 v144, v95, v144
	v_add_f32_e32 v10, v242, v10
	v_add_f32_e32 v144, v243, v144
	v_cvt_pk_bf16_f32 v144, v10, v144
	v_lshlrev_b32_e32 v10, 16, v145
	v_and_b32_e32 v145, 0xffff0000, v145
	v_add_f32_e32 v10, v96, v10
	v_add_f32_e32 v145, v97, v145
	v_add_f32_e32 v10, v244, v10
	v_add_f32_e32 v145, v245, v145
	v_cvt_pk_bf16_f32 v145, v10, v145
	global_store_dwordx4 v[224:225], v[142:145], off
	v_lshl_add_u64 v[224:225], v[224:225], 0, s[14:15]
	s_nop 0
	v_lshl_add_u64 v[222:223], v[222:223], 0, s[14:15]
	global_load_dwordx4 v[142:145], v[222:223], off offset:256
	s_waitcnt vmcnt(14)
; __device__ __forceinline__ unsigned cvt_pk_bf16(float lo, float hi) { unsigned r; asm volatile("v_cvt_pk_bf16_f32 %0, %1, %2" : "=v"(r) : "v"(lo), "v"(hi)); return r; }
; __device__ __forceinline__ float bflo(unsigned w) { return __uint_as_float(w << 16); }
; __device__ __forceinline__ float bfhi(unsigned w) { return __uint_as_float(w & 0xffff0000u); }
; __device__ __forceinline__ void epi_resid(const f32x4 (&acc)[2][2][4][2], const Unit& u, char* Cb, int ldc, const float* bias, int wr, int wc, int fr, int fq) {
;     const int col0 = u.pn * BM + wc * 32 + 8 * fq;
;     bf16_t* base = (bf16_t*)Cb + (long)(u.pm * BM + wr * 64 + fr) * ldc + col0;
; #pragma unroll
;     for (int bj = 0; bj < 2; ++bj) {
;         const f32x4 b0 = bias ? *(const f32x4*)(bias + col0 + bj * HALF) : (f32x4){0.f, 0.f, 0.f, 0.f};
;         const f32x4 b1 = bias ? *(const f32x4*)(bias + col0 + bj * HALF + 4) : (f32x4){0.f, 0.f, 0.f, 0.f};
; #pragma unroll
;         for (int ai = 0; ai < 2; ++ai)
; #pragma unroll
;             for (int m = 0; m < 4; ++m) { u32x4* q = (u32x4*)(base + (long)(ai * HALF + m * 16) * ldc + bj * HALF);
;                 const u32x4 x = *q; const f32x4 a0 = acc[ai][bj][m][0], a1 = acc[ai][bj][m][1];
;                 u32x4 w;
;                 w.x = cvt_pk_bf16(bflo(x.x) + a0[0] + b0[0], bfhi(x.x) + a0[1] + b0[1]); w.y = cvt_pk_bf16(bflo(x.y) + a0[2] + b0[2], bfhi(x.y) + a0[3] + b0[3]);
;                 w.z = cvt_pk_bf16(bflo(x.z) + a1[0] + b1[0], bfhi(x.z) + a1[1] + b1[1]); w.w = cvt_pk_bf16(bflo(x.w) + a1[2] + b1[2], bfhi(x.w) + a1[3] + b1[3]);
;                 *q = w; } }
; }
	v_lshlrev_b32_e32 v10, 16, v146
	v_and_b32_e32 v146, 0xffff0000, v146
	v_add_f32_e32 v10, v82, v10
	v_add_f32_e32 v146, v83, v146
	v_add_f32_e32 v10, v206, v10
	v_add_f32_e32 v146, v207, v146
	v_cvt_pk_bf16_f32 v146, v10, v146
	v_lshlrev_b32_e32 v10, 16, v147
	v_and_b32_e32 v147, 0xffff0000, v147
	v_add_f32_e32 v10, v84, v10
	v_add_f32_e32 v147, v85, v147
	v_add_f32_e32 v10, v208, v10
	v_add_f32_e32 v147, v209, v147
	v_cvt_pk_bf16_f32 v147, v10, v147
	v_lshlrev_b32_e32 v10, 16, v148
	v_and_b32_e32 v148, 0xffff0000, v148
	v_add_f32_e32 v10, v78, v10
	v_add_f32_e32 v148, v79, v148
	v_add_f32_e32 v10, v242, v10
	v_add_f32_e32 v148, v243, v148
	v_cvt_pk_bf16_f32 v148, v10, v148
	v_lshlrev_b32_e32 v10, 16, v149
	v_and_b32_e32 v149, 0xffff0000, v149
	v_add_f32_e32 v10, v80, v10
	v_add_f32_e32 v149, v81, v149
	v_add_f32_e32 v10, v244, v10
	v_add_f32_e32 v149, v245, v149
	v_cvt_pk_bf16_f32 v149, v10, v149
	global_store_dwordx4 v[224:225], v[146:149], off
	v_lshl_add_u64 v[224:225], v[224:225], 0, s[2:3]
	s_nop 0
	v_lshl_add_u64 v[222:223], v[222:223], 0, s[14:15]
	global_load_dwordx4 v[146:149], v[222:223], off offset:256
	s_waitcnt vmcnt(15)
	v_lshlrev_b32_e32 v10, 16, v150
	v_and_b32_e32 v150, 0xffff0000, v150
	v_add_f32_e32 v10, v66, v10
	v_add_f32_e32 v150, v67, v150
	v_add_f32_e32 v10, v206, v10
	v_add_f32_e32 v150, v207, v150
	v_cvt_pk_bf16_f32 v150, v10, v150
	v_lshlrev_b32_e32 v10, 16, v151
	v_and_b32_e32 v151, 0xffff0000, v151
	v_add_f32_e32 v10, v68, v10
	v_add_f32_e32 v151, v69, v151
	v_add_f32_e32 v10, v208, v10
	v_add_f32_e32 v151, v209, v151
	v_cvt_pk_bf16_f32 v151, v10, v151
	v_lshlrev_b32_e32 v10, 16, v152
	v_and_b32_e32 v152, 0xffff0000, v152
	v_add_f32_e32 v10, v62, v10
	v_add_f32_e32 v152, v63, v152
	v_add_f32_e32 v10, v242, v10
	v_add_f32_e32 v152, v243, v152
	v_cvt_pk_bf16_f32 v152, v10, v152
	v_lshlrev_b32_e32 v10, 16, v153
	v_and_b32_e32 v153, 0xffff0000, v153
	v_add_f32_e32 v10, v64, v10
	v_add_f32_e32 v153, v65, v153
	v_add_f32_e32 v10, v244, v10
	v_add_f32_e32 v153, v245, v153
	v_cvt_pk_bf16_f32 v153, v10, v153
	global_store_dwordx4 v[224:225], v[150:153], off
	v_lshl_add_u64 v[224:225], v[224:225], 0, s[14:15]
	s_waitcnt vmcnt(15)
	v_lshlrev_b32_e32 v10, 16, v154
	v_and_b32_e32 v154, 0xffff0000, v154
	v_add_f32_e32 v10, v50, v10
	v_add_f32_e32 v154, v51, v154
	v_add_f32_e32 v10, v206, v10
	v_add_f32_e32 v154, v207, v154
	v_cvt_pk_bf16_f32 v154, v10, v154
	v_lshlrev_b32_e32 v10, 16, v155
	v_and_b32_e32 v155, 0xffff0000, v155
	v_add_f32_e32 v10, v52, v10
	v_add_f32_e32 v155, v53, v155
	v_add_f32_e32 v10, v208, v10
	v_add_f32_e32 v155, v209, v155
	v_cvt_pk_bf16_f32 v155, v10, v155
	v_lshlrev_b32_e32 v10, 16, v156
	v_and_b32_e32 v156, 0xffff0000, v156
	v_add_f32_e32 v10, v46, v10
	v_add_f32_e32 v156, v47, v156
	v_add_f32_e32 v10, v242, v10
	v_add_f32_e32 v156, v243, v156
	v_cvt_pk_bf16_f32 v156, v10, v156
	v_lshlrev_b32_e32 v10, 16, v157
	v_and_b32_e32 v157, 0xffff0000, v157
	v_add_f32_e32 v10, v48, v10
	v_add_f32_e32 v157, v49, v157
	v_add_f32_e32 v10, v244, v10
	v_add_f32_e32 v157, v245, v157
	v_cvt_pk_bf16_f32 v157, v10, v157
	global_store_dwordx4 v[224:225], v[154:157], off
	v_lshl_add_u64 v[224:225], v[224:225], 0, s[14:15]
	s_waitcnt vmcnt(15)
	v_lshlrev_b32_e32 v10, 16, v182
	v_and_b32_e32 v182, 0xffff0000, v182
	v_add_f32_e32 v10, v34, v10
	v_add_f32_e32 v182, v35, v182
	v_add_f32_e32 v10, v206, v10
	v_add_f32_e32 v182, v207, v182
	v_cvt_pk_bf16_f32 v182, v10, v182
	v_lshlrev_b32_e32 v10, 16, v183
	v_and_b32_e32 v183, 0xffff0000, v183
	v_add_f32_e32 v10, v36, v10
	v_add_f32_e32 v183, v37, v183
	v_add_f32_e32 v10, v208, v10
	v_add_f32_e32 v183, v209, v183
	v_cvt_pk_bf16_f32 v183, v10, v183
	v_lshlrev_b32_e32 v10, 16, v184
	v_and_b32_e32 v184, 0xffff0000, v184
	v_add_f32_e32 v10, v30, v10
	v_add_f32_e32 v184, v31, v184
	v_add_f32_e32 v10, v242, v10
	v_add_f32_e32 v184, v243, v184
	v_cvt_pk_bf16_f32 v184, v10, v184
	v_lshlrev_b32_e32 v10, 16, v185
	v_and_b32_e32 v185, 0xffff0000, v185
	v_add_f32_e32 v10, v32, v10
	v_add_f32_e32 v185, v33, v185
	v_add_f32_e32 v10, v244, v10
	v_add_f32_e32 v185, v245, v185
	v_cvt_pk_bf16_f32 v185, v10, v185
	global_store_dwordx4 v[224:225], v[182:185], off
	v_lshl_add_u64 v[224:225], v[224:225], 0, s[14:15]
	s_waitcnt vmcnt(15)
	v_lshlrev_b32_e32 v10, 16, v186
	v_and_b32_e32 v186, 0xffff0000, v186
	v_add_f32_e32 v10, v18, v10
	v_add_f32_e32 v186, v19, v186
	v_add_f32_e32 v10, v206, v10
	v_add_f32_e32 v186, v207, v186
	v_cvt_pk_bf16_f32 v186, v10, v186
	v_lshlrev_b32_e32 v10, 16, v187
	v_and_b32_e32 v187, 0xffff0000, v187
	v_add_f32_e32 v10, v20, v10
	v_add_f32_e32 v187, v21, v187
	v_add_f32_e32 v10, v208, v10
	v_add_f32_e32 v187, v209, v187
	v_cvt_pk_bf16_f32 v187, v10, v187
	v_lshlrev_b32_e32 v10, 16, v188
	v_and_b32_e32 v188, 0xffff0000, v188
	v_add_f32_e32 v10, v14, v10
	v_add_f32_e32 v188, v15, v188
	v_add_f32_e32 v10, v242, v10
	v_add_f32_e32 v188, v243, v188
	v_cvt_pk_bf16_f32 v188, v10, v188
	v_lshlrev_b32_e32 v10, 16, v189
	v_and_b32_e32 v189, 0xffff0000, v189
	v_add_f32_e32 v10, v16, v10
	v_add_f32_e32 v189, v17, v189
	v_add_f32_e32 v10, v244, v10
	v_add_f32_e32 v189, v245, v189
	v_cvt_pk_bf16_f32 v189, v10, v189
	global_store_dwordx4 v[224:225], v[186:189], off
	v_mov_b64_e32 v[224:225], v[220:221]
	s_waitcnt vmcnt(15)
; __device__ __forceinline__ unsigned cvt_pk_bf16(float lo, float hi) { unsigned r; asm volatile("v_cvt_pk_bf16_f32 %0, %1, %2" : "=v"(r) : "v"(lo), "v"(hi)); return r; }
; __device__ __forceinline__ float bflo(unsigned w) { return __uint_as_float(w << 16); }
; __device__ __forceinline__ float bfhi(unsigned w) { return __uint_as_float(w & 0xffff0000u); }
; __device__ __forceinline__ void epi_resid(const f32x4 (&acc)[2][2][4][2], const Unit& u, char* Cb, int ldc, const float* bias, int wr, int wc, int fr, int fq) {
;     const int col0 = u.pn * BM + wc * 32 + 8 * fq;
;     bf16_t* base = (bf16_t*)Cb + (long)(u.pm * BM + wr * 64 + fr) * ldc + col0;
; #pragma unroll
;     for (int bj = 0; bj < 2; ++bj) {
;         const f32x4 b0 = bias ? *(const f32x4*)(bias + col0 + bj * HALF) : (f32x4){0.f, 0.f, 0.f, 0.f};
;         const f32x4 b1 = bias ? *(const f32x4*)(bias + col0 + bj * HALF + 4) : (f32x4){0.f, 0.f, 0.f, 0.f};
; #pragma unroll
;         for (int ai = 0; ai < 2; ++ai)
; #pragma unroll
;             for (int m = 0; m < 4; ++m) { u32x4* q = (u32x4*)(base + (long)(ai * HALF + m * 16) * ldc + bj * HALF);
;                 const u32x4 x = *q; const f32x4 a0 = acc[ai][bj][m][0], a1 = acc[ai][bj][m][1];
;                 u32x4 w;
;                 w.x = cvt_pk_bf16(bflo(x.x) + a0[0] + b0[0], bfhi(x.x) + a0[1] + b0[1]); w.y = cvt_pk_bf16(bflo(x.y) + a0[2] + b0[2], bfhi(x.y) + a0[3] + b0[3]);
;                 w.z = cvt_pk_bf16(bflo(x.z) + a1[0] + b1[0], bfhi(x.z) + a1[1] + b1[1]); w.w = cvt_pk_bf16(bflo(x.w) + a1[2] + b1[2], bfhi(x.w) + a1[3] + b1[3]);
;                 *q = w; } }
; }
	v_lshlrev_b32_e32 v10, 16, v190
	v_and_b32_e32 v190, 0xffff0000, v190
	v_add_f32_e32 v10, v122, v10
	v_add_f32_e32 v190, v123, v190
	v_add_f32_e32 v10, v246, v10
	v_add_f32_e32 v190, v247, v190
	v_cvt_pk_bf16_f32 v190, v10, v190
	v_lshlrev_b32_e32 v10, 16, v191
	v_and_b32_e32 v191, 0xffff0000, v191
	v_add_f32_e32 v10, v124, v10
	v_add_f32_e32 v191, v125, v191
	v_add_f32_e32 v10, v248, v10
	v_add_f32_e32 v191, v249, v191
	v_cvt_pk_bf16_f32 v191, v10, v191
	v_lshlrev_b32_e32 v10, 16, v192
	v_and_b32_e32 v192, 0xffff0000, v192
	v_add_f32_e32 v10, v118, v10
	v_add_f32_e32 v192, v119, v192
	v_add_f32_e32 v10, v250, v10
	v_add_f32_e32 v192, v251, v192
	v_cvt_pk_bf16_f32 v192, v10, v192
	v_lshlrev_b32_e32 v10, 16, v193
	v_and_b32_e32 v193, 0xffff0000, v193
	v_add_f32_e32 v10, v120, v10
	v_add_f32_e32 v193, v121, v193
	v_add_f32_e32 v10, v252, v10
	v_add_f32_e32 v193, v253, v193
	v_cvt_pk_bf16_f32 v193, v10, v193
	global_store_dwordx4 v[224:225], v[190:193], off offset:256
	v_lshl_add_u64 v[224:225], v[224:225], 0, s[14:15]
	s_waitcnt vmcnt(15)
	v_lshlrev_b32_e32 v10, 16, v194
	v_and_b32_e32 v194, 0xffff0000, v194
	v_add_f32_e32 v10, v106, v10
	v_add_f32_e32 v194, v107, v194
	v_add_f32_e32 v10, v246, v10
	v_add_f32_e32 v194, v247, v194
	v_cvt_pk_bf16_f32 v194, v10, v194
	v_lshlrev_b32_e32 v10, 16, v195
	v_and_b32_e32 v195, 0xffff0000, v195
	v_add_f32_e32 v10, v108, v10
	v_add_f32_e32 v195, v109, v195
	v_add_f32_e32 v10, v248, v10
	v_add_f32_e32 v195, v249, v195
	v_cvt_pk_bf16_f32 v195, v10, v195
	v_lshlrev_b32_e32 v10, 16, v196
	v_and_b32_e32 v196, 0xffff0000, v196
	v_add_f32_e32 v10, v102, v10
	v_add_f32_e32 v196, v103, v196
	v_add_f32_e32 v10, v250, v10
	v_add_f32_e32 v196, v251, v196
	v_cvt_pk_bf16_f32 v196, v10, v196
	v_lshlrev_b32_e32 v10, 16, v197
	v_and_b32_e32 v197, 0xffff0000, v197
	v_add_f32_e32 v10, v104, v10
	v_add_f32_e32 v197, v105, v197
	v_add_f32_e32 v10, v252, v10
	v_add_f32_e32 v197, v253, v197
	v_cvt_pk_bf16_f32 v197, v10, v197
	global_store_dwordx4 v[224:225], v[194:197], off offset:256
	v_lshl_add_u64 v[224:225], v[224:225], 0, s[14:15]
	s_waitcnt vmcnt(15)
	v_lshlrev_b32_e32 v10, 16, v198
	v_and_b32_e32 v198, 0xffff0000, v198
	v_add_f32_e32 v10, v90, v10
	v_add_f32_e32 v198, v91, v198
	v_add_f32_e32 v10, v246, v10
	v_add_f32_e32 v198, v247, v198
	v_cvt_pk_bf16_f32 v198, v10, v198
	v_lshlrev_b32_e32 v10, 16, v199
	v_and_b32_e32 v199, 0xffff0000, v199
	v_add_f32_e32 v10, v92, v10
	v_add_f32_e32 v199, v93, v199
	v_add_f32_e32 v10, v248, v10
	v_add_f32_e32 v199, v249, v199
	v_cvt_pk_bf16_f32 v199, v10, v199
	v_lshlrev_b32_e32 v10, 16, v200
	v_and_b32_e32 v200, 0xffff0000, v200
	v_add_f32_e32 v10, v86, v10
	v_add_f32_e32 v200, v87, v200
	v_add_f32_e32 v10, v250, v10
	v_add_f32_e32 v200, v251, v200
	v_cvt_pk_bf16_f32 v200, v10, v200
	v_lshlrev_b32_e32 v10, 16, v201
	v_and_b32_e32 v201, 0xffff0000, v201
	v_add_f32_e32 v10, v88, v10
	v_add_f32_e32 v201, v89, v201
	v_add_f32_e32 v10, v252, v10
	v_add_f32_e32 v201, v253, v201
	v_cvt_pk_bf16_f32 v201, v10, v201
	global_store_dwordx4 v[224:225], v[198:201], off offset:256
	v_lshl_add_u64 v[224:225], v[224:225], 0, s[14:15]
	s_waitcnt vmcnt(15)
	v_lshlrev_b32_e32 v10, 16, v202
	v_and_b32_e32 v202, 0xffff0000, v202
	v_add_f32_e32 v10, v74, v10
	v_add_f32_e32 v202, v75, v202
	v_add_f32_e32 v10, v246, v10
	v_add_f32_e32 v202, v247, v202
	v_cvt_pk_bf16_f32 v202, v10, v202
	v_lshlrev_b32_e32 v10, 16, v203
	v_and_b32_e32 v203, 0xffff0000, v203
	v_add_f32_e32 v10, v76, v10
	v_add_f32_e32 v203, v77, v203
	v_add_f32_e32 v10, v248, v10
	v_add_f32_e32 v203, v249, v203
	v_cvt_pk_bf16_f32 v203, v10, v203
	v_lshlrev_b32_e32 v10, 16, v204
	v_and_b32_e32 v204, 0xffff0000, v204
	v_add_f32_e32 v10, v70, v10
	v_add_f32_e32 v204, v71, v204
	v_add_f32_e32 v10, v250, v10
	v_add_f32_e32 v204, v251, v204
	v_cvt_pk_bf16_f32 v204, v10, v204
	v_lshlrev_b32_e32 v10, 16, v205
	v_and_b32_e32 v205, 0xffff0000, v205
	v_add_f32_e32 v10, v72, v10
	v_add_f32_e32 v205, v73, v205
	v_add_f32_e32 v10, v252, v10
	v_add_f32_e32 v205, v253, v205
	v_cvt_pk_bf16_f32 v205, v10, v205
	global_store_dwordx4 v[224:225], v[202:205], off offset:256
	v_lshl_add_u64 v[224:225], v[224:225], 0, s[2:3]
	s_waitcnt vmcnt(14)
; __device__ __forceinline__ unsigned cvt_pk_bf16(float lo, float hi) { unsigned r; asm volatile("v_cvt_pk_bf16_f32 %0, %1, %2" : "=v"(r) : "v"(lo), "v"(hi)); return r; }
; __device__ __forceinline__ float bflo(unsigned w) { return __uint_as_float(w << 16); }
; __device__ __forceinline__ float bfhi(unsigned w) { return __uint_as_float(w & 0xffff0000u); }
; __device__ __forceinline__ void epi_resid(const f32x4 (&acc)[2][2][4][2], const Unit& u, char* Cb, int ldc, const float* bias, int wr, int wc, int fr, int fq) {
;     const int col0 = u.pn * BM + wc * 32 + 8 * fq;
;     bf16_t* base = (bf16_t*)Cb + (long)(u.pm * BM + wr * 64 + fr) * ldc + col0;
; #pragma unroll
;     for (int bj = 0; bj < 2; ++bj) {
;         const f32x4 b0 = bias ? *(const f32x4*)(bias + col0 + bj * HALF) : (f32x4){0.f, 0.f, 0.f, 0.f};
;         const f32x4 b1 = bias ? *(const f32x4*)(bias + col0 + bj * HALF + 4) : (f32x4){0.f, 0.f, 0.f, 0.f};
; #pragma unroll
;         for (int ai = 0; ai < 2; ++ai)
; #pragma unroll
;             for (int m = 0; m < 4; ++m) { u32x4* q = (u32x4*)(base + (long)(ai * HALF + m * 16) * ldc + bj * HALF);
;                 const u32x4 x = *q; const f32x4 a0 = acc[ai][bj][m][0], a1 = acc[ai][bj][m][1];
;                 u32x4 w;
;                 w.x = cvt_pk_bf16(bflo(x.x) + a0[0] + b0[0], bfhi(x.x) + a0[1] + b0[1]); w.y = cvt_pk_bf16(bflo(x.y) + a0[2] + b0[2], bfhi(x.y) + a0[3] + b0[3]);
;                 w.z = cvt_pk_bf16(bflo(x.z) + a1[0] + b1[0], bfhi(x.z) + a1[1] + b1[1]); w.w = cvt_pk_bf16(bflo(x.w) + a1[2] + b1[2], bfhi(x.w) + a1[3] + b1[3]);
;                 *q = w; } }
; }
	v_lshlrev_b32_e32 v10, 16, v134
	v_and_b32_e32 v134, 0xffff0000, v134
	v_add_f32_e32 v10, v58, v10
	v_add_f32_e32 v134, v59, v134
	v_add_f32_e32 v10, v246, v10
	v_add_f32_e32 v134, v247, v134
	v_cvt_pk_bf16_f32 v134, v10, v134
	v_lshlrev_b32_e32 v10, 16, v135
	v_and_b32_e32 v135, 0xffff0000, v135
	v_add_f32_e32 v10, v60, v10
	v_add_f32_e32 v135, v61, v135
	v_add_f32_e32 v10, v248, v10
	v_add_f32_e32 v135, v249, v135
	v_cvt_pk_bf16_f32 v135, v10, v135
	v_lshlrev_b32_e32 v10, 16, v136
	v_and_b32_e32 v136, 0xffff0000, v136
	v_add_f32_e32 v10, v54, v10
	v_add_f32_e32 v136, v55, v136
	v_add_f32_e32 v10, v250, v10
	v_add_f32_e32 v136, v251, v136
	v_cvt_pk_bf16_f32 v136, v10, v136
	v_lshlrev_b32_e32 v10, 16, v137
	v_and_b32_e32 v137, 0xffff0000, v137
	v_add_f32_e32 v10, v56, v10
	v_add_f32_e32 v137, v57, v137
	v_add_f32_e32 v10, v252, v10
	v_add_f32_e32 v137, v253, v137
	v_cvt_pk_bf16_f32 v137, v10, v137
	global_store_dwordx4 v[224:225], v[134:137], off offset:256
	v_lshl_add_u64 v[224:225], v[224:225], 0, s[14:15]
	s_waitcnt vmcnt(13)
	v_lshlrev_b32_e32 v10, 16, v138
	v_and_b32_e32 v138, 0xffff0000, v138
	v_add_f32_e32 v10, v42, v10
	v_add_f32_e32 v138, v43, v138
	v_add_f32_e32 v10, v246, v10
	v_add_f32_e32 v138, v247, v138
	v_cvt_pk_bf16_f32 v138, v10, v138
	v_lshlrev_b32_e32 v10, 16, v139
	v_and_b32_e32 v139, 0xffff0000, v139
	v_add_f32_e32 v10, v44, v10
	v_add_f32_e32 v139, v45, v139
	v_add_f32_e32 v10, v248, v10
	v_add_f32_e32 v139, v249, v139
	v_cvt_pk_bf16_f32 v139, v10, v139
	v_lshlrev_b32_e32 v10, 16, v140
	v_and_b32_e32 v140, 0xffff0000, v140
	v_add_f32_e32 v10, v38, v10
	v_add_f32_e32 v140, v39, v140
	v_add_f32_e32 v10, v250, v10
	v_add_f32_e32 v140, v251, v140
	v_cvt_pk_bf16_f32 v140, v10, v140
	v_lshlrev_b32_e32 v10, 16, v141
	v_and_b32_e32 v141, 0xffff0000, v141
	v_add_f32_e32 v10, v40, v10
	v_add_f32_e32 v141, v41, v141
	v_add_f32_e32 v10, v252, v10
	v_add_f32_e32 v141, v253, v141
	v_cvt_pk_bf16_f32 v141, v10, v141
	global_store_dwordx4 v[224:225], v[138:141], off offset:256
	v_lshl_add_u64 v[224:225], v[224:225], 0, s[14:15]
	s_waitcnt vmcnt(12)
	v_lshlrev_b32_e32 v10, 16, v142
	v_and_b32_e32 v142, 0xffff0000, v142
	v_add_f32_e32 v10, v26, v10
	v_add_f32_e32 v142, v27, v142
	v_add_f32_e32 v10, v246, v10
	v_add_f32_e32 v142, v247, v142
	v_cvt_pk_bf16_f32 v142, v10, v142
	v_lshlrev_b32_e32 v10, 16, v143
	v_and_b32_e32 v143, 0xffff0000, v143
	v_add_f32_e32 v10, v28, v10
	v_add_f32_e32 v143, v29, v143
	v_add_f32_e32 v10, v248, v10
	v_add_f32_e32 v143, v249, v143
	v_cvt_pk_bf16_f32 v143, v10, v143
	v_lshlrev_b32_e32 v10, 16, v144
	v_and_b32_e32 v144, 0xffff0000, v144
	v_add_f32_e32 v10, v22, v10
	v_add_f32_e32 v144, v23, v144
	v_add_f32_e32 v10, v250, v10
	v_add_f32_e32 v144, v251, v144
	v_cvt_pk_bf16_f32 v144, v10, v144
	v_lshlrev_b32_e32 v10, 16, v145
	v_and_b32_e32 v145, 0xffff0000, v145
	v_add_f32_e32 v10, v24, v10
	v_add_f32_e32 v145, v25, v145
	v_add_f32_e32 v10, v252, v10
	v_add_f32_e32 v145, v253, v145
	v_cvt_pk_bf16_f32 v145, v10, v145
	global_store_dwordx4 v[224:225], v[142:145], off offset:256
	v_lshl_add_u64 v[224:225], v[224:225], 0, s[14:15]
	s_waitcnt vmcnt(11)
	v_lshlrev_b32_e32 v10, 16, v146
	v_and_b32_e32 v146, 0xffff0000, v146
	v_add_f32_e32 v10, v4, v10
	v_add_f32_e32 v146, v5, v146
	v_add_f32_e32 v10, v246, v10
	v_add_f32_e32 v146, v247, v146
	v_cvt_pk_bf16_f32 v146, v10, v146
	v_lshlrev_b32_e32 v10, 16, v147
	v_and_b32_e32 v147, 0xffff0000, v147
	v_add_f32_e32 v10, v6, v10
	v_add_f32_e32 v147, v7, v147
	v_add_f32_e32 v10, v248, v10
	v_add_f32_e32 v147, v249, v147
	v_cvt_pk_bf16_f32 v147, v10, v147
	v_lshlrev_b32_e32 v10, 16, v148
	v_and_b32_e32 v148, 0xffff0000, v148
	v_add_f32_e32 v10, v0, v10
	v_add_f32_e32 v148, v1, v148
	v_add_f32_e32 v10, v250, v10
	v_add_f32_e32 v148, v251, v148
	v_cvt_pk_bf16_f32 v148, v10, v148
	v_lshlrev_b32_e32 v10, 16, v149
	v_and_b32_e32 v149, 0xffff0000, v149
	v_add_f32_e32 v10, v2, v10
	v_add_f32_e32 v149, v3, v149
	v_add_f32_e32 v10, v252, v10
	v_add_f32_e32 v149, v253, v149
	v_cvt_pk_bf16_f32 v149, v10, v149
	global_store_dwordx4 v[224:225], v[146:149], off offset:256
	s_mov_b64 s[72:73], 0
